# ln2: the two wave-sum butterflies per token done with DPP and permlane swaps instead of 12 ds_bpermute round trips (same pairings)
# speedup vs baseline: 1.0007x; 1.0007x over previous
.LBB0_1393:
	v_mov_b32_e32 v76, v65
	v_mov_b32_e32 v77, v62
	v_mov_b32_e32 v78, v64
	v_mov_b32_e32 v79, v63
	v_pk_add_f32 v[76:77], v[76:77], v[78:79]
	v_mov_b32_e32 v78, v61
	v_mov_b32_e32 v79, v58
	v_mov_b32_e32 v80, v60
	v_mov_b32_e32 v81, v59
	v_pk_add_f32 v[78:79], v[78:79], v[80:81]
	v_add_f32_e32 v40, v76, v77
	v_pk_add_f32 v[78:79], v[78:79], v[78:79] op_sel_hi:[0,1]
	v_add_f32_e32 v77, 0, v40
	v_add_f32_e32 v81, v56, v57
	v_add_f32_e32 v83, v54, v55
	v_mov_b32_e32 v80, v50
	v_mov_b32_e32 v82, v51
	v_mov_b32_e32 v78, v52
	v_mov_b32_e32 v76, v53
	v_pk_add_f32 v[80:81], v[80:81], v[82:83]
	v_pk_add_f32 v[76:77], v[78:79], v[76:77]
	s_ashr_i32 s81, s80, 31
	v_pk_add_f32 v[76:77], v[80:81], v[76:77]
	s_nop 0
	v_add_f32_e32 v40, v76, v77
	s_nop 1
	v_add_f32_dpp v40, v40, v40 quad_perm:[1,0,3,2] row_mask:0xf bank_mask:0xf
	s_nop 1
	v_add_f32_dpp v40, v40, v40 quad_perm:[2,3,0,1] row_mask:0xf bank_mask:0xf
	s_nop 1
	v_add_f32_dpp v40, v40, v40 row_half_mirror row_mask:0xf bank_mask:0xf
	s_nop 1
	v_add_f32_dpp v40, v40, v40 row_mirror row_mask:0xf bank_mask:0xf
	v_mov_b32_e32 v76, v40
	s_nop 1
	v_permlane16_swap_b32_e32 v76, v40
	v_add_f32_e32 v40, v40, v76
	v_mov_b32_e32 v76, v40
	s_nop 1
	v_permlane32_swap_b32_e32 v76, v40
	v_add_f32_e32 v86, v40, v76
	v_fmamk_f32 v65, v86, 0xba800000, v65
	v_fmamk_f32 v64, v86, 0xba800000, v64
	v_fmamk_f32 v63, v86, 0xba800000, v63
	v_fmamk_f32 v62, v86, 0xba800000, v62
	v_pk_mul_f32 v[76:77], v[62:63], v[62:63]
	v_pk_mul_f32 v[78:79], v[64:65], v[64:65]
	v_fmamk_f32 v61, v86, 0xba800000, v61
	v_fmamk_f32 v60, v86, 0xba800000, v60
	v_fmamk_f32 v59, v86, 0xba800000, v59
	v_pk_mov_b32 v[80:81], v[78:79], v[76:77] op_sel:[1,0]
	v_mov_b32_e32 v79, v77
	v_fmamk_f32 v58, v86, 0xba800000, v58
	v_pk_add_f32 v[76:77], v[80:81], v[78:79]
	v_pk_mul_f32 v[78:79], v[58:59], v[58:59]
	v_pk_mul_f32 v[80:81], v[60:61], v[60:61]
	v_fmamk_f32 v56, v86, 0xba800000, v56
	v_pk_mov_b32 v[82:83], v[80:81], v[78:79] op_sel:[1,0]
	v_mov_b32_e32 v81, v79
	v_pk_add_f32 v[78:79], v[82:83], v[80:81]
	v_fmamk_f32 v57, v86, 0xba800000, v57
	v_fmamk_f32 v80, v86, 0xba800000, v54
	v_mul_f32_e32 v40, v56, v56
	v_fmamk_f32 v81, v86, 0xba800000, v55
	v_pk_fma_f32 v[54:55], v[56:57], v[56:57], v[40:41] op_sel_hi:[1,1,0]
	v_mul_f32_e32 v40, v80, v80
	v_pk_add_f32 v[76:77], v[76:77], v[76:77] op_sel_hi:[0,1]
	v_pk_add_f32 v[78:79], v[78:79], v[78:79] op_sel_hi:[0,1]
	v_pk_fma_f32 v[82:83], v[80:81], v[80:81], v[40:41] op_sel_hi:[1,1,0]
	v_fmamk_f32 v85, v86, 0xba800000, v53
	v_fmamk_f32 v84, v86, 0xba800000, v52
	v_fmamk_f32 v51, v86, 0xba800000, v51
	v_fmac_f32_e32 v50, 0xba800000, v86
	v_mul_f32_e32 v54, v50, v50
	v_mul_f32_e32 v82, v51, v51
	v_mul_f32_e32 v76, v84, v84
	v_mul_f32_e32 v78, v85, v85
	v_pk_add_f32 v[52:53], v[54:55], v[82:83]
	v_pk_add_f32 v[54:55], v[76:77], v[78:79]
	s_nop 0
	v_pk_add_f32 v[52:53], v[52:53], v[54:55]
	s_nop 0
	v_add_f32_e32 v40, v52, v53
	s_nop 1
	v_add_f32_dpp v40, v40, v40 quad_perm:[1,0,3,2] row_mask:0xf bank_mask:0xf
	s_nop 1
	v_add_f32_dpp v40, v40, v40 quad_perm:[2,3,0,1] row_mask:0xf bank_mask:0xf
	s_nop 1
	v_add_f32_dpp v40, v40, v40 row_half_mirror row_mask:0xf bank_mask:0xf
	s_nop 1
	v_add_f32_dpp v40, v40, v40 row_mirror row_mask:0xf bank_mask:0xf
	v_mov_b32_e32 v52, v40
	s_nop 1
	v_permlane16_swap_b32_e32 v52, v40
	v_add_f32_e32 v40, v40, v52
	v_mov_b32_e32 v52, v40
	s_nop 1
	v_permlane32_swap_b32_e32 v52, v40
	v_add_f32_e32 v40, v40, v52
	v_fmamk_f32 v40, v40, 0x3a800000, v73
	v_mul_f32_e32 v52, 0x4f800000, v40
	v_cmp_gt_f32_e32 vcc, s5, v40
	s_nop 1
	v_cndmask_b32_e32 v40, v40, v52, vcc
	v_sqrt_f32_e32 v52, v40
	s_nop 0
	v_add_u32_e32 v53, -1, v52
	v_add_u32_e32 v54, 1, v52
	v_fma_f32 v55, -v53, v52, v40
	v_fma_f32 v76, -v54, v52, v40
	v_cmp_ge_f32_e64 s[2:3], 0, v55
	s_nop 1
	v_cndmask_b32_e64 v52, v52, v53, s[2:3]
	v_cmp_lt_f32_e64 s[2:3], 0, v76
	s_nop 1
	v_cndmask_b32_e64 v52, v52, v54, s[2:3]
	v_mul_f32_e32 v53, 0x37800000, v52
	v_cndmask_b32_e32 v52, v52, v53, vcc
	v_cmp_class_f32_e32 vcc, v40, v74
	s_nop 1
	v_cndmask_b32_e32 v40, v52, v40, vcc
	v_div_scale_f32 v52, s[2:3], v40, v40, 1.0
	v_rcp_f32_e32 v53, v52
	s_lshl_b64 s[2:3], s[80:81], 12
	v_lshl_add_u64 v[76:77], v[38:39], 0, s[2:3]
	s_mov_b32 s80, s8
	v_fma_f32 v54, -v52, v53, 1.0
	v_fmac_f32_e32 v53, v54, v53
	v_div_scale_f32 v54, vcc, 1.0, v40, 1.0
	v_mul_f32_e32 v55, v54, v53
	v_fma_f32 v78, -v52, v55, v54
	v_fmac_f32_e32 v55, v78, v53
	v_fma_f32 v52, -v52, v55, v54
	v_div_fmas_f32 v52, v52, v53, v55
	v_div_fixup_f32 v40, v52, v40, 1.0
	v_pk_mul_f32 v[52:53], v[64:65], v[40:41] op_sel_hi:[1,0]
	v_pk_mul_f32 v[54:55], v[62:63], v[40:41] op_sel_hi:[1,0]
	v_pk_fma_f32 v[52:53], v[0:1], v[52:53], v[8:9]
	v_pk_fma_f32 v[54:55], v[2:3], v[54:55], v[10:11]
	global_store_dwordx4 v[76:77], v[52:55], off
	v_pk_mul_f32 v[50:51], v[50:51], v[40:41] op_sel_hi:[1,0]
	s_and_b64 vcc, exec, s[10:11]
	v_pk_mul_f32 v[52:53], v[60:61], v[40:41] op_sel_hi:[1,0]
	v_pk_mul_f32 v[54:55], v[58:59], v[40:41] op_sel_hi:[1,0]
	v_pk_fma_f32 v[52:53], v[4:5], v[52:53], v[12:13]
	v_pk_fma_f32 v[54:55], v[6:7], v[54:55], v[14:15]
	global_store_dwordx4 v[76:77], v[52:55], off offset:1024
	v_pk_fma_f32 v[50:51], v[20:21], v[50:51], v[28:29]
	s_nop 0
	v_pk_mul_f32 v[52:53], v[56:57], v[40:41] op_sel_hi:[1,0]
	v_pk_mul_f32 v[54:55], v[80:81], v[40:41] op_sel_hi:[1,0]
	v_pk_fma_f32 v[52:53], v[16:17], v[52:53], v[24:25]
	v_pk_fma_f32 v[54:55], v[18:19], v[54:55], v[26:27]
	global_store_dwordx4 v[76:77], v[52:55], off offset:2048
	s_waitcnt vmcnt(6)
	v_mov_b32_e32 v56, v42
	v_mov_b32_e32 v57, v43
	v_pk_mul_f32 v[52:53], v[84:85], v[40:41] op_sel_hi:[1,0]
	s_waitcnt vmcnt(5)
	v_mov_b32_e32 v54, v44
	v_pk_fma_f32 v[52:53], v[22:23], v[52:53], v[30:31]
	global_store_dwordx4 v[76:77], v[50:53], off offset:3072
	s_waitcnt vmcnt(4)
	v_mov_b32_e32 v76, v75
	v_mov_b32_e32 v55, v45
	v_mov_b32_e32 v52, v46
	v_mov_b32_e32 v53, v47
	v_mov_b32_e32 v50, v48
	v_mov_b32_e32 v51, v49
	s_cbranch_vccnz .LBB0_1404
